# GLA stage 1: decay-projection weight rows kept in registers across a workgroup's units with the same head (28 of 34 loads skipped)
# speedup vs baseline: 1.0073x; 1.0011x over previous
; #define LAS __attribute__((address_space(3)))
; DI float bflo(unsigned w) { return __uint_as_float(w << 16); }
; DI float bfhi(unsigned w) { return __uint_as_float(w & 0xffff0000u); }
; DI void gla_stage1(const Ctx& c0, int layer, int unit, LAS unsigned char* lds) {
;     ...
;     const int cc = tid >> 3, ch = tid & 7;
; #pragma unroll
;     for (int it = 0; it < 2; ++it) { const int idx = tid + 512 * it, vc_ = idx & 15, c_ = idx >> 4;
;         const u32x4 v = *(const u32x4*)(gv + (row0 + c_) * 512 + h * 128 + vc_ * 8);
;         *(LAS u32x4*)(lds + G1_VI + (vc_ >> 2) * 4096 + c_ * 64 + (vc_ & 3) * 16) = v; }
;     {
;         float ga[16];
;         { const u32x4 g0 = *(const u32x4*)(misc + (row0 + cc) * 64 + 32), g1 = *(const u32x4*)(misc + (row0 + cc) * 64 + 40);
;           ga[0] = bflo(g0.x); ga[1] = bfhi(g0.x); ga[2] = bflo(g0.y); ga[3] = bfhi(g0.y); ga[4] = bflo(g0.z); ga[5] = bfhi(g0.z); ga[6] = bflo(g0.w); ga[7] = bfhi(g0.w);
;           ga[8] = bflo(g1.x); ga[9] = bfhi(g1.x); ga[10] = bflo(g1.y); ga[11] = bfhi(g1.y); ga[12] = bflo(g1.z); ga[13] = bfhi(g1.z); ga[14] = bflo(g1.w); ga[15] = bfhi(g1.w); }
;         f32x4 a0 = *(const f32x4*)(ba + 8 * ch), a1 = *(const f32x4*)(ba + 8 * ch + 4);
;         const float* wap = Wa + 8 * ch; asm volatile("" : "+v"(wap));
; #pragma unroll
;         for (int rr = 0; rr < 16; ++rr) { const f32x4 w0 = *(const f32x4*)(wap + rr * 256), w1 = *(const f32x4*)(wap + rr * 256 + 4); a0 += w0 * ga[rr]; a1 += w1 * ga[rr]; }
.LBB0_400:
	s_waitcnt lgkmcnt(0)
	s_bfe_u32 s100, s80, 0x20006
	s_cmp_eq_u32 s100, s101
	s_mov_b32 s101, s100
	s_cbranch_scc1 .Lg1b_l0
	s_mov_b64 s[98:99], 0x1000
	s_mov_b64 s[82:83], s[86:87]
	s_mov_b64 vcc, 0x1b500000
	v_mov_b32_e32 v86, v151
	v_add_u32_e32 v94, 0x200, v86
	v_ashrrev_i32_e32 v78, 4, v94
	v_ashrrev_i32_e32 v79, 31, v78
	v_and_b32_e32 v102, 7, v86
	s_mov_b64 s[72:73], s[84:85]
	s_ashr_i32 s72, s80, 8
	s_ashr_i32 s73, s72, 31
	v_and_b32_e32 v88, 15, v86
	v_lshlrev_b32_e32 v48, 4, v88
	v_lshlrev_b32_e32 v3, 4, v86
	v_ashrrev_i32_e32 v8, 4, v86
	v_ashrrev_i32_e32 v9, 31, v8
	v_and_b32_e32 v11, 48, v3
	s_lshl_b32 s0, s80, 6
	s_bfe_u32 s89, s80, 0x20006
	s_lshl_b64 s[84:85], s[72:73], 12
	s_and_b32 s0, s0, 0xfc0
	s_or_b32 s84, s84, s0
	v_lshl_add_u64 v[68:69], s[84:85], 0, v[78:79]
	v_lshlrev_b64 v[76:77], 10, v[68:69]
	s_lshl_b32 s0, s89, 8
	s_add_u32 s72, s82, s0
	s_addc_u32 s73, s83, 0
	v_lshl_add_u64 v[100:101], s[72:73], 0, v[48:49]
	v_lshlrev_b32_e32 v48, 5, v102
	s_mov_b64 s[72:73], 0xf500000
	v_lshl_add_u64 v[6:7], v[100:101], 0, s[72:73]
	v_lshl_add_u64 v[74:75], v[6:7], 0, v[76:77]
	global_load_dwordx4 v[228:231], v[74:75], off
	s_add_u32 s72, s76, s0
	s_addc_u32 s73, s77, 0
	v_lshl_add_u64 v[24:25], s[72:73], 0, v[48:49]
	global_load_dwordx4 v[200:203], v[24:25], off offset:16
	global_load_dwordx4 v[204:207], v[24:25], off
	global_load_dwordx4 v[146:149], v[24:25], off offset:1040
	global_load_dwordx4 v[220:223], v[24:25], off offset:1024
	global_load_dwordx4 v[224:227], v[24:25], off offset:2064
	global_load_dwordx4 v[236:239], v[24:25], off offset:2048
	global_load_dwordx4 v[240:243], v[24:25], off offset:3088
	global_load_dwordx4 v[72:75], v[24:25], off offset:3072
	s_add_u32 s86, s78, s0
	s_addc_u32 s87, s79, 0
	global_load_dwordx4 v[208:211], v48, s[86:87]
	global_load_dwordx4 v[212:215], v48, s[86:87] offset:16
	v_lshl_add_u64 v[244:245], v[24:25], 0, s[98:99]
	global_load_dwordx4 v[168:171], v[244:245], off offset:3088
	global_load_dwordx4 v[118:121], v[244:245], off offset:3072
	global_load_dwordx4 v[114:117], v[244:245], off offset:2064
	global_load_dwordx4 v[110:113], v[244:245], off offset:2048
	global_load_dwordx4 v[106:109], v[244:245], off offset:1040
	global_load_dwordx4 v[96:99], v[244:245], off offset:1024
	global_load_dwordx4 v[68:71], v[244:245], off
	v_lshl_add_u64 v[246:247], v[244:245], 0, s[98:99]
	global_load_dwordx4 v[90:93], v[246:247], off offset:2064
	global_load_dwordx4 v[142:145], v[246:247], off offset:2048
	global_load_dwordx4 v[138:141], v[246:247], off offset:1040
	global_load_dwordx4 v[134:137], v[246:247], off offset:1024
	global_load_dwordx4 v[130:133], v[246:247], off offset:16
	global_load_dwordx4 v[126:129], v[246:247], off
	global_load_dwordx4 v[160:163], v[246:247], off offset:3088
	global_load_dwordx4 v[156:159], v[246:247], off offset:3072
	v_lshl_add_u64 v[248:249], v[246:247], 0, s[98:99]
	global_load_dwordx4 v[216:219], v[248:249], off offset:3072
	global_load_dwordx4 v[196:199], v[248:249], off offset:2064
	global_load_dwordx4 v[180:183], v[248:249], off offset:2048
	global_load_dwordx4 v[176:179], v[248:249], off offset:1040
	global_load_dwordx4 v[172:175], v[248:249], off offset:1024
	global_load_dwordx4 v[122:125], v[248:249], off offset:16
	global_load_dwordx4 v[164:167], v[248:249], off
	v_lshlrev_b32_e32 v2, 10, v86
	v_and_b32_e32 v2, 0x3000, v2
	v_add3_u32 v13, 0, v2, v11
	v_lshl_add_u64 v[2:3], s[84:85], 0, v[8:9]
	v_lshlrev_b64 v[2:3], 10, v[2:3]
	v_lshl_add_u64 v[2:3], v[6:7], 0, v[2:3]
	global_load_dwordx4 v[82:85], v[2:3], off
	v_lshl_add_u32 v6, v78, 6, v13
	global_load_dwordx4 v[76:79], v[244:245], off offset:16
	v_lshl_add_u32 v8, v8, 6, v13
	s_waitcnt vmcnt(1)
	ds_write_b128 v8, v[82:85] offset:43264
	ds_write_b128 v6, v[228:231] offset:43264
	v_ashrrev_i32_e32 v12, 3, v86
	v_ashrrev_i32_e32 v13, 31, v12
	v_lshl_add_u64 v[2:3], s[84:85], 0, v[12:13]
	v_lshlrev_b64 v[4:5], 7, v[2:3]
	v_lshl_add_u64 v[4:5], s[82:83], 0, v[4:5]
	v_lshl_add_u64 v[8:9], v[4:5], 0, vcc
	global_load_dwordx4 v[4:7], v[8:9], off offset:64
	global_load_dwordx4 v[232:235], v[8:9], off offset:80
	s_waitcnt vmcnt(0)
	v_and_b32_e32 v20, 0xffff0000, v232
	v_lshlrev_b32_e32 v18, 16, v233
	v_lshlrev_b32_e32 v22, 16, v232
	v_and_b32_e32 v26, 0xffff0000, v7
	v_lshlrev_b32_e32 v28, 16, v7
	v_and_b32_e32 v30, 0xffff0000, v6
	v_lshlrev_b32_e32 v66, 16, v6
	v_and_b32_e32 v64, 0xffff0000, v5
	v_lshlrev_b32_e32 v62, 16, v5
	v_and_b32_e32 v60, 0xffff0000, v4
	v_lshlrev_b32_e32 v58, 16, v4
	v_pk_fma_f32 v[54:55], v[58:59], v[200:201], v[212:213] op_sel_hi:[0,1,1]
	v_pk_fma_f32 v[54:55], v[60:61], v[146:147], v[54:55] op_sel_hi:[0,1,1]
	v_pk_fma_f32 v[54:55], v[62:63], v[224:225], v[54:55] op_sel_hi:[0,1,1]
	v_pk_fma_f32 v[54:55], v[64:65], v[240:241], v[54:55] op_sel_hi:[0,1,1]
	v_pk_fma_f32 v[54:55], v[66:67], v[76:77], v[54:55] op_sel_hi:[0,1,1]
	v_pk_fma_f32 v[56:57], v[58:59], v[202:203], v[214:215] op_sel_hi:[0,1,1]
	v_pk_fma_f32 v[56:57], v[60:61], v[148:149], v[56:57] op_sel_hi:[0,1,1]
	v_pk_fma_f32 v[56:57], v[62:63], v[226:227], v[56:57] op_sel_hi:[0,1,1]
	v_pk_fma_f32 v[56:57], v[64:65], v[242:243], v[56:57] op_sel_hi:[0,1,1]
	v_pk_fma_f32 v[56:57], v[66:67], v[78:79], v[56:57] op_sel_hi:[0,1,1]
	v_pk_fma_f32 v[56:57], v[30:31], v[108:109], v[56:57] op_sel_hi:[0,1,1]
	v_pk_fma_f32 v[40:41], v[28:29], v[116:117], v[56:57] op_sel_hi:[0,1,1]
	v_pk_fma_f32 v[40:41], v[26:27], v[170:171], v[40:41] op_sel_hi:[0,1,1]
	v_pk_fma_f32 v[42:43], v[58:59], v[204:205], v[208:209] op_sel_hi:[0,1,1]
	v_pk_fma_f32 v[42:43], v[60:61], v[220:221], v[42:43] op_sel_hi:[0,1,1]
; DI void gla_stage1(const Ctx& c0, int layer, int unit, LAS unsigned char* lds) {
;     ...
;         const float* wap = Wa + 8 * ch; asm volatile("" : "+v"(wap));
; #pragma unroll
;         for (int rr = 0; rr < 16; ++rr) { const f32x4 w0 = *(const f32x4*)(wap + rr * 256), w1 = *(const f32x4*)(wap + rr * 256 + 4); a0 += w0 * ga[rr]; a1 += w1 * ga[rr]; }
; #pragma unroll
;         for (int j = 0; j < 8; ++j) { const float x = j < 4 ? a0[j & 3] : a1[j & 3];
;             const float ls = fminf(x, 0.f) - __logf(1.f + __expf(-fabsf(x)));
	v_pk_fma_f32 v[42:43], v[62:63], v[236:237], v[42:43] op_sel_hi:[0,1,1]
	v_pk_fma_f32 v[42:43], v[64:65], v[72:73], v[42:43] op_sel_hi:[0,1,1]
	v_pk_fma_f32 v[42:43], v[66:67], v[68:69], v[42:43] op_sel_hi:[0,1,1]
	v_pk_fma_f32 v[42:43], v[30:31], v[96:97], v[42:43] op_sel_hi:[0,1,1]
	v_pk_fma_f32 v[42:43], v[28:29], v[110:111], v[42:43] op_sel_hi:[0,1,1]
	v_pk_fma_f32 v[42:43], v[26:27], v[118:119], v[42:43] op_sel_hi:[0,1,1]
	v_pk_fma_f32 v[42:43], v[22:23], v[126:127], v[42:43] op_sel_hi:[0,1,1]
	v_pk_fma_f32 v[44:45], v[58:59], v[206:207], v[210:211] op_sel_hi:[0,1,1]
	v_pk_fma_f32 v[44:45], v[60:61], v[222:223], v[44:45] op_sel_hi:[0,1,1]
	v_pk_fma_f32 v[44:45], v[62:63], v[238:239], v[44:45] op_sel_hi:[0,1,1]
	v_pk_fma_f32 v[44:45], v[64:65], v[74:75], v[44:45] op_sel_hi:[0,1,1]
	v_pk_fma_f32 v[44:45], v[66:67], v[70:71], v[44:45] op_sel_hi:[0,1,1]
	v_pk_fma_f32 v[44:45], v[30:31], v[98:99], v[44:45] op_sel_hi:[0,1,1]
	v_pk_fma_f32 v[30:31], v[30:31], v[106:107], v[54:55] op_sel_hi:[0,1,1]
	v_pk_fma_f32 v[44:45], v[28:29], v[112:113], v[44:45] op_sel_hi:[0,1,1]
	v_pk_fma_f32 v[38:39], v[28:29], v[114:115], v[30:31] op_sel_hi:[0,1,1]
	v_pk_fma_f32 v[30:31], v[26:27], v[120:121], v[44:45] op_sel_hi:[0,1,1]
	v_pk_fma_f32 v[30:31], v[22:23], v[128:129], v[30:31] op_sel_hi:[0,1,1]
	v_pk_fma_f32 v[30:31], v[20:21], v[136:137], v[30:31] op_sel_hi:[0,1,1]
	v_pk_fma_f32 v[38:39], v[26:27], v[168:169], v[38:39] op_sel_hi:[0,1,1]
	v_pk_fma_f32 v[38:39], v[22:23], v[130:131], v[38:39] op_sel_hi:[0,1,1]
	v_pk_fma_f32 v[34:35], v[20:21], v[138:139], v[38:39] op_sel_hi:[0,1,1]
	v_pk_fma_f32 v[22:23], v[22:23], v[132:133], v[40:41] op_sel_hi:[0,1,1]
	v_pk_fma_f32 v[40:41], v[20:21], v[134:135], v[42:43] op_sel_hi:[0,1,1]
	v_pk_fma_f32 v[36:37], v[20:21], v[140:141], v[22:23] op_sel_hi:[0,1,1]
	v_pk_fma_f32 v[38:39], v[18:19], v[142:143], v[40:41] op_sel_hi:[0,1,1]
	v_pk_fma_f32 v[22:23], v[18:19], v[144:145], v[30:31] op_sel_hi:[0,1,1]
	v_pk_fma_f32 v[30:31], v[18:19], v[90:91], v[34:35] op_sel_hi:[0,1,1]
	v_pk_fma_f32 v[34:35], v[18:19], v[92:93], v[36:37] op_sel_hi:[0,1,1]
	global_load_dwordx4 v[18:21], v[248:249], off offset:3088
	s_movk_i32 s0, 0x104
	v_lshl_add_u32 v33, v86, 2, 0
	v_mul_lo_u32 v13, v12, s0
	v_add3_u32 v13, 0, v13, v48
	s_movk_i32 s0, 0x820
	v_and_b32_e32 v16, 0xffff0000, v233
	v_lshlrev_b32_e32 v14, 16, v234
	v_and_b32_e32 v8, 0xffff0000, v234
	v_lshlrev_b32_e32 v4, 16, v235
	v_and_b32_e32 v6, 0xffff0000, v235
	v_lshl_add_u64 v[58:59], v[24:25], 0, s[98:99]
	v_lshl_add_u64 v[44:45], v[58:59], 0, s[98:99]
	v_lshl_add_u64 v[24:25], v[44:45], 0, s[98:99]
	v_pk_fma_f32 v[36:37], v[16:17], v[158:159], v[22:23] op_sel_hi:[0,1,1]
	v_pk_fma_f32 v[38:39], v[16:17], v[156:157], v[38:39] op_sel_hi:[0,1,1]
	v_pk_fma_f32 v[28:29], v[16:17], v[162:163], v[34:35] op_sel_hi:[0,1,1]
	v_pk_fma_f32 v[26:27], v[16:17], v[160:161], v[30:31] op_sel_hi:[0,1,1]
	v_pk_fma_f32 v[30:31], v[14:15], v[164:165], v[38:39] op_sel_hi:[0,1,1]
	v_pk_fma_f32 v[34:35], v[14:15], v[166:167], v[36:37] op_sel_hi:[0,1,1]
	v_pk_fma_f32 v[26:27], v[14:15], v[122:123], v[26:27] op_sel_hi:[0,1,1]
	v_pk_fma_f32 v[22:23], v[14:15], v[124:125], v[28:29] op_sel_hi:[0,1,1]
	v_pk_fma_f32 v[28:29], v[8:9], v[174:175], v[34:35] op_sel_hi:[0,1,1]
	v_pk_fma_f32 v[30:31], v[8:9], v[172:173], v[30:31] op_sel_hi:[0,1,1]
	v_pk_fma_f32 v[22:23], v[8:9], v[178:179], v[22:23] op_sel_hi:[0,1,1]
	v_pk_fma_f32 v[8:9], v[8:9], v[176:177], v[26:27] op_sel_hi:[0,1,1]
	v_pk_fma_f32 v[26:27], v[4:5], v[180:181], v[30:31] op_sel_hi:[0,1,1]
	v_pk_fma_f32 v[28:29], v[4:5], v[182:183], v[28:29] op_sel_hi:[0,1,1]
	v_pk_fma_f32 v[30:31], v[4:5], v[196:197], v[8:9] op_sel_hi:[0,1,1]
	v_pk_fma_f32 v[4:5], v[4:5], v[198:199], v[22:23] op_sel_hi:[0,1,1]
	v_pk_fma_f32 v[14:15], v[6:7], v[216:217], v[26:27] op_sel_hi:[0,1,1]
	v_pk_fma_f32 v[8:9], v[6:7], v[218:219], v[28:29] op_sel_hi:[0,1,1]
	v_min_f32_e32 v16, 0, v14
	v_mul_f32_e64 v14, |v14|, s93
	v_exp_f32_e32 v14, v14
	s_waitcnt vmcnt(0)
; DI void gla_stage1(const Ctx& c0, int layer, int unit, LAS unsigned char* lds) {
;     ...
;         for (int j = 0; j < 8; ++j) { const float x = j < 4 ? a0[j & 3] : a1[j & 3];
;             const float ls = fminf(x, 0.f) - __logf(1.f + __expf(-fabsf(x)));
;             LA[cc * 65 + 8 * ch + j] = ls * (1.f / 16.f); }
;     }
;     __syncthreads();
;     {
;         const int d = tid & 63, part = tid >> 6; float v[8]; float run = 0.f;
; #pragma unroll
;         for (int j = 0; j < 8; ++j) { run += LA[(8 * part + j) * 65 + d]; v[j] = run; }
	v_pk_fma_f32 v[4:5], v[6:7], v[20:21], v[4:5] op_sel_hi:[0,1,1]
	v_pk_fma_f32 v[6:7], v[6:7], v[18:19], v[30:31] op_sel_hi:[0,1,1]
	v_mov_b32_e32 v20, 0
	v_add_f32_e32 v14, 1.0, v14
	v_cmp_gt_f32_e32 vcc, s94, v14
	v_mov_b32_e32 v21, 0
	s_nop 0
	v_cndmask_b32_e64 v17, 0, 32, vcc
	v_ldexp_f32 v14, v14, v17
	v_log_f32_e32 v14, v14
	s_nop 0
	v_mul_f32_e32 v17, 0x3f317217, v14
	v_fma_f32 v17, v14, s95, -v17
	v_fmac_f32_e32 v17, 0x3377d1cf, v14
	v_fmac_f32_e32 v17, 0x3f317217, v14
	v_cmp_lt_f32_e64 s[72:73], |v14|, s96
	s_nop 1
	v_cndmask_b32_e64 v14, v14, v17, s[72:73]
	v_cndmask_b32_e32 v17, 0, v47, vcc
	v_sub_f32_e32 v14, v14, v17
	v_min_f32_e32 v17, 0, v15
	v_mul_f32_e64 v15, |v15|, s93
	v_exp_f32_e32 v15, v15
	s_nop 0
	v_add_f32_e32 v15, 1.0, v15
	v_cmp_gt_f32_e32 vcc, s94, v15
	s_nop 1
	v_cndmask_b32_e64 v18, 0, 32, vcc
	v_ldexp_f32 v15, v15, v18
	v_log_f32_e32 v15, v15
	s_nop 0
	v_mul_f32_e32 v18, 0x3f317217, v15
	v_fma_f32 v18, v15, s95, -v18
	v_fmac_f32_e32 v18, 0x3377d1cf, v15
	v_fmac_f32_e32 v18, 0x3f317217, v15
	v_cmp_lt_f32_e64 s[72:73], |v15|, s96
	s_nop 1
	v_cndmask_b32_e64 v15, v15, v18, s[72:73]
	v_cndmask_b32_e32 v18, 0, v47, vcc
	v_sub_f32_e32 v15, v15, v18
	v_pk_add_f32 v[14:15], v[16:17], v[14:15] neg_lo:[0,1] neg_hi:[0,1]
	v_ashrrev_i32_e32 v17, 6, v86
	v_pk_mul_f32 v[14:15], v[14:15], s[8:9] op_sel_hi:[1,0]
	ds_write2_b32 v13, v14, v15 offset1:1
	v_min_f32_e32 v14, 0, v8
	v_mul_f32_e64 v8, |v8|, s93
	v_exp_f32_e32 v8, v8
	s_nop 0
	v_add_f32_e32 v8, 1.0, v8
	v_cmp_gt_f32_e32 vcc, s94, v8
	s_nop 1
	v_cndmask_b32_e64 v15, 0, 32, vcc
	v_ldexp_f32 v8, v8, v15
	v_log_f32_e32 v8, v8
	s_nop 0
	v_mul_f32_e32 v15, 0x3f317217, v8
	v_fma_f32 v15, v8, s95, -v15
	v_fmac_f32_e32 v15, 0x3377d1cf, v8
	v_fmac_f32_e32 v15, 0x3f317217, v8
	v_cmp_lt_f32_e64 s[72:73], |v8|, s96
	s_nop 1
	v_cndmask_b32_e64 v8, v8, v15, s[72:73]
	v_cndmask_b32_e32 v15, 0, v47, vcc
	v_sub_f32_e32 v8, v8, v15
	v_min_f32_e32 v15, 0, v9
	v_mul_f32_e64 v9, |v9|, s93
	v_exp_f32_e32 v9, v9
	s_nop 0
	v_add_f32_e32 v9, 1.0, v9
	v_cmp_gt_f32_e32 vcc, s94, v9
	s_nop 1
	v_cndmask_b32_e64 v16, 0, 32, vcc
	v_ldexp_f32 v9, v9, v16
	v_log_f32_e32 v9, v9
	s_nop 0
	v_mul_f32_e32 v16, 0x3f317217, v9
	v_fma_f32 v16, v9, s95, -v16
	v_fmac_f32_e32 v16, 0x3377d1cf, v9
	v_fmac_f32_e32 v16, 0x3f317217, v9
	v_cmp_lt_f32_e64 s[72:73], |v9|, s96
	s_nop 1
	v_cndmask_b32_e64 v9, v9, v16, s[72:73]
	v_cndmask_b32_e32 v16, 0, v47, vcc
	v_sub_f32_e32 v9, v9, v16
	v_pk_add_f32 v[8:9], v[14:15], v[8:9] neg_lo:[0,1] neg_hi:[0,1]
	v_pk_mul_f32 v[8:9], v[8:9], s[8:9] op_sel_hi:[1,0]
	ds_write2_b32 v13, v8, v9 offset0:2 offset1:3
	v_min_f32_e32 v8, 0, v6
	v_mul_f32_e64 v6, |v6|, s93
	v_exp_f32_e32 v6, v6
	s_nop 0
	v_add_f32_e32 v6, 1.0, v6
	v_cmp_gt_f32_e32 vcc, s94, v6
	s_nop 1
	v_cndmask_b32_e64 v9, 0, 32, vcc
	v_ldexp_f32 v6, v6, v9
	v_log_f32_e32 v6, v6
	s_nop 0
	v_mul_f32_e32 v9, 0x3f317217, v6
	v_fma_f32 v9, v6, s95, -v9
	v_fmac_f32_e32 v9, 0x3377d1cf, v6
	v_fmac_f32_e32 v9, 0x3f317217, v6
	v_cmp_lt_f32_e64 s[72:73], |v6|, s96
	s_nop 1
	v_cndmask_b32_e64 v6, v6, v9, s[72:73]
	v_cndmask_b32_e32 v9, 0, v47, vcc
	v_sub_f32_e32 v6, v6, v9
	v_min_f32_e32 v9, 0, v7
	v_mul_f32_e64 v7, |v7|, s93
	v_exp_f32_e32 v7, v7
	s_nop 0
	v_add_f32_e32 v7, 1.0, v7
	v_cmp_gt_f32_e32 vcc, s94, v7
	s_nop 1
	v_cndmask_b32_e64 v14, 0, 32, vcc
	v_ldexp_f32 v7, v7, v14
	v_log_f32_e32 v7, v7
	s_nop 0
	v_mul_f32_e32 v14, 0x3f317217, v7
	v_fma_f32 v14, v7, s95, -v14
	v_fmac_f32_e32 v14, 0x3377d1cf, v7
	v_fmac_f32_e32 v14, 0x3f317217, v7
	v_cmp_lt_f32_e64 s[72:73], |v7|, s96
	s_nop 1
	v_cndmask_b32_e64 v7, v7, v14, s[72:73]
	v_cndmask_b32_e32 v14, 0, v47, vcc
	v_sub_f32_e32 v7, v7, v14
	v_pk_add_f32 v[6:7], v[8:9], v[6:7] neg_lo:[0,1] neg_hi:[0,1]
	v_pk_mul_f32 v[6:7], v[6:7], s[8:9] op_sel_hi:[1,0]
	ds_write2_b32 v13, v6, v7 offset0:4 offset1:5
	v_min_f32_e32 v6, 0, v4
	v_mul_f32_e64 v4, |v4|, s93
	v_exp_f32_e32 v4, v4
	s_nop 0
	v_add_f32_e32 v4, 1.0, v4
	v_cmp_gt_f32_e32 vcc, s94, v4
	s_nop 1
	v_cndmask_b32_e64 v7, 0, 32, vcc
	v_ldexp_f32 v4, v4, v7
	v_log_f32_e32 v4, v4
	s_nop 0
	v_mul_f32_e32 v7, 0x3f317217, v4
	v_fma_f32 v7, v4, s95, -v7
	v_fmac_f32_e32 v7, 0x3377d1cf, v4
	v_fmac_f32_e32 v7, 0x3f317217, v4
	v_cmp_lt_f32_e64 s[72:73], |v4|, s96
	s_nop 1
	v_cndmask_b32_e64 v4, v4, v7, s[72:73]
	v_cndmask_b32_e32 v7, 0, v47, vcc
	v_sub_f32_e32 v4, v4, v7
	v_min_f32_e32 v7, 0, v5
	v_mul_f32_e64 v5, |v5|, s93
	v_exp_f32_e32 v5, v5
	s_nop 0
	v_add_f32_e32 v5, 1.0, v5
	v_cmp_gt_f32_e32 vcc, s94, v5
	s_nop 1
	v_cndmask_b32_e64 v8, 0, 32, vcc
	v_ldexp_f32 v5, v5, v8
	v_log_f32_e32 v5, v5
	s_nop 0
	v_mul_f32_e32 v8, 0x3f317217, v5
	v_fma_f32 v8, v5, s95, -v8
	v_fmac_f32_e32 v8, 0x3377d1cf, v5
	v_fmac_f32_e32 v8, 0x3f317217, v5
	v_cmp_lt_f32_e64 s[72:73], |v5|, s96
	s_nop 1
	v_cndmask_b32_e64 v5, v5, v8, s[72:73]
	v_cndmask_b32_e32 v8, 0, v47, vcc
	v_sub_f32_e32 v5, v5, v8
	v_pk_add_f32 v[4:5], v[6:7], v[4:5] neg_lo:[0,1] neg_hi:[0,1]
	v_cmp_lt_i32_e32 vcc, 0, v17
	v_pk_mul_f32 v[4:5], v[4:5], s[8:9] op_sel_hi:[1,0]
	ds_write2_b32 v13, v4, v5 offset0:6 offset1:7
	v_and_b32_e32 v4, 63, v86
	v_lshl_add_u32 v14, v4, 2, 0
	v_mul_lo_u32 v4, v17, s0
	v_add_u32_e32 v4, v14, v4
	v_mov_b32_e32 v10, v86
	v_mov_b32_e32 v80, v94
	v_mov_b32_e32 v32, v102
	s_waitcnt vmcnt(0) lgkmcnt(0)
	s_branch .Lg1j_l0

; #define LAS __attribute__((address_space(3)))
; DI float bflo(unsigned w) { return __uint_as_float(w << 16); }
; DI float bfhi(unsigned w) { return __uint_as_float(w & 0xffff0000u); }
; DI void gla_stage1(const Ctx& c0, int layer, int unit, LAS unsigned char* lds) {
;     ...
;     const int cc = tid >> 3, ch = tid & 7;
; #pragma unroll
;     for (int it = 0; it < 2; ++it) { const int idx = tid + 512 * it, vc_ = idx & 15, c_ = idx >> 4;
;         const u32x4 v = *(const u32x4*)(gv + (row0 + c_) * 512 + h * 128 + vc_ * 8);
;         *(LAS u32x4*)(lds + G1_VI + (vc_ >> 2) * 4096 + c_ * 64 + (vc_ & 3) * 16) = v; }
;     {
;         float ga[16];
;         { const u32x4 g0 = *(const u32x4*)(misc + (row0 + cc) * 64 + 32), g1 = *(const u32x4*)(misc + (row0 + cc) * 64 + 40);
;           ga[0] = bflo(g0.x); ga[1] = bfhi(g0.x); ga[2] = bflo(g0.y); ga[3] = bfhi(g0.y); ga[4] = bflo(g0.z); ga[5] = bfhi(g0.z); ga[6] = bflo(g0.w); ga[7] = bfhi(g0.w);
;           ga[8] = bflo(g1.x); ga[9] = bfhi(g1.x); ga[10] = bflo(g1.y); ga[11] = bfhi(g1.y); ga[12] = bflo(g1.z); ga[13] = bfhi(g1.z); ga[14] = bflo(g1.w); ga[15] = bfhi(g1.w); }
;         f32x4 a0 = *(const f32x4*)(ba + 8 * ch), a1 = *(const f32x4*)(ba + 8 * ch + 4);
;         const float* wap = Wa + 8 * ch; asm volatile("" : "+v"(wap));
; #pragma unroll
;         for (int rr = 0; rr < 16; ++rr) { const f32x4 w0 = *(const f32x4*)(wap + rr * 256), w1 = *(const f32x4*)(wap + rr * 256 + 4); a0 += w0 * ga[rr]; a1 += w1 * ga[rr]; }
.LBB0_1016:
	s_waitcnt lgkmcnt(0)
	s_bfe_u32 s100, s82, 0x20006
	s_cmp_eq_u32 s100, s101
	s_mov_b32 s101, s100
	s_cbranch_scc1 .Lg1b_l1
	s_mov_b64 s[98:99], 0x1000
	s_mov_b64 vcc, 0x1b500000
	v_mov_b32_e32 v82, v151
	v_add_u32_e32 v94, 0x200, v82
	v_ashrrev_i32_e32 v78, 4, v94
	v_ashrrev_i32_e32 v79, 31, v78
	v_and_b32_e32 v102, 7, v82
	s_mov_b64 s[74:75], s[84:85]
	s_mov_b64 s[84:85], s[86:87]
	s_ashr_i32 s74, s82, 8
	s_ashr_i32 s75, s74, 31
	v_and_b32_e32 v88, 15, v82
	v_lshlrev_b32_e32 v48, 4, v88
	v_lshlrev_b32_e32 v3, 4, v82
	v_ashrrev_i32_e32 v8, 4, v82
	v_ashrrev_i32_e32 v9, 31, v8
	v_and_b32_e32 v11, 48, v3
	s_lshl_b32 s0, s82, 6
	s_bfe_u32 s81, s82, 0x20006
	s_lshl_b64 s[86:87], s[74:75], 12
	s_and_b32 s0, s0, 0xfc0
	s_or_b32 s86, s86, s0
	v_lshl_add_u64 v[76:77], s[86:87], 0, v[78:79]
	v_lshlrev_b64 v[74:75], 10, v[76:77]
	s_lshl_b32 s0, s81, 8
	s_add_u32 s74, s84, s0
	s_addc_u32 s75, s85, 0
	v_lshl_add_u64 v[100:101], s[74:75], 0, v[48:49]
	v_lshlrev_b32_e32 v48, 5, v102
	s_mov_b64 s[74:75], 0xf500000
	v_lshl_add_u64 v[6:7], v[100:101], 0, s[74:75]
	v_lshl_add_u64 v[80:81], v[6:7], 0, v[74:75]
	global_load_dwordx4 v[228:231], v[80:81], off
	s_add_u32 s74, s33, s0
	s_addc_u32 s75, s77, 0
	v_lshl_add_u64 v[24:25], s[74:75], 0, v[48:49]
	global_load_dwordx4 v[196:199], v[24:25], off offset:16
	global_load_dwordx4 v[200:203], v[24:25], off
	global_load_dwordx4 v[142:145], v[24:25], off offset:1040
	global_load_dwordx4 v[216:219], v[24:25], off offset:1024
	global_load_dwordx4 v[220:223], v[24:25], off offset:2064
	global_load_dwordx4 v[236:239], v[24:25], off offset:2048
	global_load_dwordx4 v[240:243], v[24:25], off offset:3088
	global_load_dwordx4 v[72:75], v[24:25], off offset:3072
	s_add_u32 s88, s78, s0
	s_addc_u32 s89, s79, 0
	global_load_dwordx4 v[204:207], v48, s[88:89] offset:1024
	global_load_dwordx4 v[208:211], v48, s[88:89] offset:1040
	v_lshl_add_u64 v[244:245], v[24:25], 0, s[98:99]
	global_load_dwordx4 v[164:167], v[244:245], off offset:3088
	global_load_dwordx4 v[114:117], v[244:245], off offset:3072
	global_load_dwordx4 v[110:113], v[244:245], off offset:2064
	global_load_dwordx4 v[106:109], v[244:245], off offset:2048
	global_load_dwordx4 v[96:99], v[244:245], off offset:1040
	global_load_dwordx4 v[90:93], v[244:245], off offset:1024
	global_load_dwordx4 v[68:71], v[244:245], off
	v_lshl_add_u64 v[246:247], v[244:245], 0, s[98:99]
	global_load_dwordx4 v[84:87], v[246:247], off offset:2064
	global_load_dwordx4 v[138:141], v[246:247], off offset:2048
	global_load_dwordx4 v[134:137], v[246:247], off offset:1040
	global_load_dwordx4 v[130:133], v[246:247], off offset:1024
	global_load_dwordx4 v[126:129], v[246:247], off offset:16
	global_load_dwordx4 v[122:125], v[246:247], off
	global_load_dwordx4 v[156:159], v[246:247], off offset:3088
	global_load_dwordx4 v[146:149], v[246:247], off offset:3072
	v_lshl_add_u64 v[248:249], v[246:247], 0, s[98:99]
	global_load_dwordx4 v[212:215], v[248:249], off offset:3072
	global_load_dwordx4 v[180:183], v[248:249], off offset:2064
	global_load_dwordx4 v[176:179], v[248:249], off offset:2048
	global_load_dwordx4 v[172:175], v[248:249], off offset:1040
	global_load_dwordx4 v[168:171], v[248:249], off offset:1024
	global_load_dwordx4 v[118:121], v[248:249], off offset:16
	global_load_dwordx4 v[160:163], v[248:249], off
	v_lshlrev_b32_e32 v2, 10, v82
	v_and_b32_e32 v2, 0x3000, v2
	v_add3_u32 v13, 0, v2, v11
	v_lshl_add_u64 v[2:3], s[86:87], 0, v[8:9]
	v_lshlrev_b64 v[2:3], 10, v[2:3]
	v_lshl_add_u64 v[2:3], v[6:7], 0, v[2:3]
	global_load_dwordx4 v[224:227], v[2:3], off
	v_lshl_add_u32 v6, v78, 6, v13
	global_load_dwordx4 v[76:79], v[244:245], off offset:16
	v_lshl_add_u32 v8, v8, 6, v13
	s_waitcnt vmcnt(1)
	ds_write_b128 v8, v[224:227] offset:43264
	ds_write_b128 v6, v[228:231] offset:43264
	v_ashrrev_i32_e32 v12, 3, v82
	v_ashrrev_i32_e32 v13, 31, v12
	v_lshl_add_u64 v[2:3], s[86:87], 0, v[12:13]
	v_lshlrev_b64 v[4:5], 7, v[2:3]
	v_lshl_add_u64 v[4:5], s[84:85], 0, v[4:5]
	v_lshl_add_u64 v[8:9], v[4:5], 0, vcc
	global_load_dwordx4 v[4:7], v[8:9], off offset:64
	global_load_dwordx4 v[232:235], v[8:9], off offset:80
	s_waitcnt vmcnt(0)
	v_and_b32_e32 v20, 0xffff0000, v232
	v_lshlrev_b32_e32 v18, 16, v233
	v_lshlrev_b32_e32 v22, 16, v232
	v_and_b32_e32 v26, 0xffff0000, v7
	v_lshlrev_b32_e32 v28, 16, v7
	v_and_b32_e32 v30, 0xffff0000, v6
	v_lshlrev_b32_e32 v66, 16, v6
	v_and_b32_e32 v64, 0xffff0000, v5
	v_lshlrev_b32_e32 v62, 16, v5
	v_and_b32_e32 v60, 0xffff0000, v4
	v_lshlrev_b32_e32 v58, 16, v4
	v_pk_fma_f32 v[54:55], v[58:59], v[196:197], v[208:209] op_sel_hi:[0,1,1]
	v_pk_fma_f32 v[54:55], v[60:61], v[142:143], v[54:55] op_sel_hi:[0,1,1]
	v_pk_fma_f32 v[54:55], v[62:63], v[220:221], v[54:55] op_sel_hi:[0,1,1]
	v_pk_fma_f32 v[54:55], v[64:65], v[240:241], v[54:55] op_sel_hi:[0,1,1]
	v_pk_fma_f32 v[54:55], v[66:67], v[76:77], v[54:55] op_sel_hi:[0,1,1]
	v_pk_fma_f32 v[56:57], v[58:59], v[198:199], v[210:211] op_sel_hi:[0,1,1]
	v_pk_fma_f32 v[56:57], v[60:61], v[144:145], v[56:57] op_sel_hi:[0,1,1]
	v_pk_fma_f32 v[56:57], v[62:63], v[222:223], v[56:57] op_sel_hi:[0,1,1]
	v_pk_fma_f32 v[56:57], v[64:65], v[242:243], v[56:57] op_sel_hi:[0,1,1]
	v_pk_fma_f32 v[56:57], v[66:67], v[78:79], v[56:57] op_sel_hi:[0,1,1]
	v_pk_fma_f32 v[56:57], v[30:31], v[98:99], v[56:57] op_sel_hi:[0,1,1]
	v_pk_fma_f32 v[40:41], v[28:29], v[112:113], v[56:57] op_sel_hi:[0,1,1]
	v_pk_fma_f32 v[40:41], v[26:27], v[166:167], v[40:41] op_sel_hi:[0,1,1]
	v_pk_fma_f32 v[42:43], v[58:59], v[200:201], v[204:205] op_sel_hi:[0,1,1]
	v_pk_fma_f32 v[42:43], v[60:61], v[216:217], v[42:43] op_sel_hi:[0,1,1]
; DI void gla_stage1(const Ctx& c0, int layer, int unit, LAS unsigned char* lds) {
;     ...
;         const float* wap = Wa + 8 * ch; asm volatile("" : "+v"(wap));
; #pragma unroll
;         for (int rr = 0; rr < 16; ++rr) { const f32x4 w0 = *(const f32x4*)(wap + rr * 256), w1 = *(const f32x4*)(wap + rr * 256 + 4); a0 += w0 * ga[rr]; a1 += w1 * ga[rr]; }
; #pragma unroll
;         for (int j = 0; j < 8; ++j) { const float x = j < 4 ? a0[j & 3] : a1[j & 3];
;             const float ls = fminf(x, 0.f) - __logf(1.f + __expf(-fabsf(x)));
	v_pk_fma_f32 v[42:43], v[62:63], v[236:237], v[42:43] op_sel_hi:[0,1,1]
	v_pk_fma_f32 v[42:43], v[64:65], v[72:73], v[42:43] op_sel_hi:[0,1,1]
	v_pk_fma_f32 v[42:43], v[66:67], v[68:69], v[42:43] op_sel_hi:[0,1,1]
	v_pk_fma_f32 v[42:43], v[30:31], v[90:91], v[42:43] op_sel_hi:[0,1,1]
	v_pk_fma_f32 v[42:43], v[28:29], v[106:107], v[42:43] op_sel_hi:[0,1,1]
	v_pk_fma_f32 v[42:43], v[26:27], v[114:115], v[42:43] op_sel_hi:[0,1,1]
	v_pk_fma_f32 v[42:43], v[22:23], v[122:123], v[42:43] op_sel_hi:[0,1,1]
	v_pk_fma_f32 v[44:45], v[58:59], v[202:203], v[206:207] op_sel_hi:[0,1,1]
	v_pk_fma_f32 v[44:45], v[60:61], v[218:219], v[44:45] op_sel_hi:[0,1,1]
	v_pk_fma_f32 v[44:45], v[62:63], v[238:239], v[44:45] op_sel_hi:[0,1,1]
	v_pk_fma_f32 v[44:45], v[64:65], v[74:75], v[44:45] op_sel_hi:[0,1,1]
	v_pk_fma_f32 v[44:45], v[66:67], v[70:71], v[44:45] op_sel_hi:[0,1,1]
	v_pk_fma_f32 v[44:45], v[30:31], v[92:93], v[44:45] op_sel_hi:[0,1,1]
	v_pk_fma_f32 v[30:31], v[30:31], v[96:97], v[54:55] op_sel_hi:[0,1,1]
	v_pk_fma_f32 v[44:45], v[28:29], v[108:109], v[44:45] op_sel_hi:[0,1,1]
	v_pk_fma_f32 v[38:39], v[28:29], v[110:111], v[30:31] op_sel_hi:[0,1,1]
	v_pk_fma_f32 v[30:31], v[26:27], v[116:117], v[44:45] op_sel_hi:[0,1,1]
	v_pk_fma_f32 v[30:31], v[22:23], v[124:125], v[30:31] op_sel_hi:[0,1,1]
	v_pk_fma_f32 v[30:31], v[20:21], v[132:133], v[30:31] op_sel_hi:[0,1,1]
	v_pk_fma_f32 v[38:39], v[26:27], v[164:165], v[38:39] op_sel_hi:[0,1,1]
	v_pk_fma_f32 v[38:39], v[22:23], v[126:127], v[38:39] op_sel_hi:[0,1,1]
	v_pk_fma_f32 v[34:35], v[20:21], v[134:135], v[38:39] op_sel_hi:[0,1,1]
	v_pk_fma_f32 v[22:23], v[22:23], v[128:129], v[40:41] op_sel_hi:[0,1,1]
	v_pk_fma_f32 v[40:41], v[20:21], v[130:131], v[42:43] op_sel_hi:[0,1,1]
	v_pk_fma_f32 v[36:37], v[20:21], v[136:137], v[22:23] op_sel_hi:[0,1,1]
	v_pk_fma_f32 v[38:39], v[18:19], v[138:139], v[40:41] op_sel_hi:[0,1,1]
	v_pk_fma_f32 v[22:23], v[18:19], v[140:141], v[30:31] op_sel_hi:[0,1,1]
	v_pk_fma_f32 v[30:31], v[18:19], v[84:85], v[34:35] op_sel_hi:[0,1,1]
	v_pk_fma_f32 v[34:35], v[18:19], v[86:87], v[36:37] op_sel_hi:[0,1,1]
	global_load_dwordx4 v[18:21], v[248:249], off offset:3088
	s_movk_i32 s0, 0x104
	v_lshl_add_u32 v33, v82, 2, 0
	v_mul_lo_u32 v13, v12, s0
	v_add3_u32 v13, 0, v13, v48
	s_movk_i32 s0, 0x820
	v_and_b32_e32 v16, 0xffff0000, v233
	v_lshlrev_b32_e32 v14, 16, v234
	v_and_b32_e32 v8, 0xffff0000, v234
	v_lshlrev_b32_e32 v4, 16, v235
	v_and_b32_e32 v6, 0xffff0000, v235
	v_lshl_add_u64 v[58:59], v[24:25], 0, s[98:99]
	v_lshl_add_u64 v[44:45], v[58:59], 0, s[98:99]
	v_lshl_add_u64 v[24:25], v[44:45], 0, s[98:99]
	v_pk_fma_f32 v[36:37], v[16:17], v[148:149], v[22:23] op_sel_hi:[0,1,1]
	v_pk_fma_f32 v[38:39], v[16:17], v[146:147], v[38:39] op_sel_hi:[0,1,1]
	v_pk_fma_f32 v[28:29], v[16:17], v[158:159], v[34:35] op_sel_hi:[0,1,1]
	v_pk_fma_f32 v[26:27], v[16:17], v[156:157], v[30:31] op_sel_hi:[0,1,1]
	v_pk_fma_f32 v[30:31], v[14:15], v[160:161], v[38:39] op_sel_hi:[0,1,1]
	v_pk_fma_f32 v[34:35], v[14:15], v[162:163], v[36:37] op_sel_hi:[0,1,1]
	v_pk_fma_f32 v[26:27], v[14:15], v[118:119], v[26:27] op_sel_hi:[0,1,1]
	v_pk_fma_f32 v[22:23], v[14:15], v[120:121], v[28:29] op_sel_hi:[0,1,1]
	v_pk_fma_f32 v[28:29], v[8:9], v[170:171], v[34:35] op_sel_hi:[0,1,1]
	v_pk_fma_f32 v[30:31], v[8:9], v[168:169], v[30:31] op_sel_hi:[0,1,1]
	v_pk_fma_f32 v[22:23], v[8:9], v[174:175], v[22:23] op_sel_hi:[0,1,1]
	v_pk_fma_f32 v[8:9], v[8:9], v[172:173], v[26:27] op_sel_hi:[0,1,1]
	v_pk_fma_f32 v[26:27], v[4:5], v[176:177], v[30:31] op_sel_hi:[0,1,1]
	v_pk_fma_f32 v[28:29], v[4:5], v[178:179], v[28:29] op_sel_hi:[0,1,1]
	v_pk_fma_f32 v[30:31], v[4:5], v[180:181], v[8:9] op_sel_hi:[0,1,1]
	v_pk_fma_f32 v[4:5], v[4:5], v[182:183], v[22:23] op_sel_hi:[0,1,1]
	v_pk_fma_f32 v[14:15], v[6:7], v[212:213], v[26:27] op_sel_hi:[0,1,1]
	v_pk_fma_f32 v[8:9], v[6:7], v[214:215], v[28:29] op_sel_hi:[0,1,1]
	v_min_f32_e32 v16, 0, v14
	v_mul_f32_e64 v14, |v14|, s96
	v_exp_f32_e32 v14, v14
	s_waitcnt vmcnt(0)
; DI void gla_stage1(const Ctx& c0, int layer, int unit, LAS unsigned char* lds) {
;     ...
;         for (int j = 0; j < 8; ++j) { const float x = j < 4 ? a0[j & 3] : a1[j & 3];
;             const float ls = fminf(x, 0.f) - __logf(1.f + __expf(-fabsf(x)));
;             LA[cc * 65 + 8 * ch + j] = ls * (1.f / 16.f); }
;     }
;     __syncthreads();
;     {
;         const int d = tid & 63, part = tid >> 6; float v[8]; float run = 0.f;
; #pragma unroll
;         for (int j = 0; j < 8; ++j) { run += LA[(8 * part + j) * 65 + d]; v[j] = run; }
	v_pk_fma_f32 v[4:5], v[6:7], v[20:21], v[4:5] op_sel_hi:[0,1,1]
	v_pk_fma_f32 v[6:7], v[6:7], v[18:19], v[30:31] op_sel_hi:[0,1,1]
	v_mov_b32_e32 v20, 0
	v_add_f32_e32 v14, 1.0, v14
	v_cmp_gt_f32_e32 vcc, s97, v14
	v_mov_b32_e32 v21, 0
	s_nop 0
	v_cndmask_b32_e64 v17, 0, 32, vcc
	v_ldexp_f32 v14, v14, v17
	v_log_f32_e32 v14, v14
	s_nop 0
	v_mul_f32_e32 v17, 0x3f317217, v14
	v_fma_f32 v17, v14, s92, -v17
	v_fmac_f32_e32 v17, 0x3377d1cf, v14
	v_fmac_f32_e32 v17, 0x3f317217, v14
	v_cmp_lt_f32_e64 s[74:75], |v14|, s8
	s_nop 1
	v_cndmask_b32_e64 v14, v14, v17, s[74:75]
	v_cndmask_b32_e32 v17, 0, v47, vcc
	v_sub_f32_e32 v14, v14, v17
	v_min_f32_e32 v17, 0, v15
	v_mul_f32_e64 v15, |v15|, s96
	v_exp_f32_e32 v15, v15
	s_nop 0
	v_add_f32_e32 v15, 1.0, v15
	v_cmp_gt_f32_e32 vcc, s97, v15
	s_nop 1
	v_cndmask_b32_e64 v18, 0, 32, vcc
	v_ldexp_f32 v15, v15, v18
	v_log_f32_e32 v15, v15
	s_nop 0
	v_mul_f32_e32 v18, 0x3f317217, v15
	v_fma_f32 v18, v15, s92, -v18
	v_fmac_f32_e32 v18, 0x3377d1cf, v15
	v_fmac_f32_e32 v18, 0x3f317217, v15
	v_cmp_lt_f32_e64 s[74:75], |v15|, s8
	s_nop 1
	v_cndmask_b32_e64 v15, v15, v18, s[74:75]
	v_cndmask_b32_e32 v18, 0, v47, vcc
	v_sub_f32_e32 v15, v15, v18
	v_pk_add_f32 v[14:15], v[16:17], v[14:15] neg_lo:[0,1] neg_hi:[0,1]
	v_ashrrev_i32_e32 v17, 6, v82
	v_pk_mul_f32 v[14:15], v[14:15], s[6:7] op_sel_hi:[1,0]
	ds_write2_b32 v13, v14, v15 offset1:1
	v_min_f32_e32 v14, 0, v8
	v_mul_f32_e64 v8, |v8|, s96
	v_exp_f32_e32 v8, v8
	s_nop 0
	v_add_f32_e32 v8, 1.0, v8
	v_cmp_gt_f32_e32 vcc, s97, v8
	s_nop 1
	v_cndmask_b32_e64 v15, 0, 32, vcc
	v_ldexp_f32 v8, v8, v15
	v_log_f32_e32 v8, v8
	s_nop 0
	v_mul_f32_e32 v15, 0x3f317217, v8
	v_fma_f32 v15, v8, s92, -v15
	v_fmac_f32_e32 v15, 0x3377d1cf, v8
	v_fmac_f32_e32 v15, 0x3f317217, v8
	v_cmp_lt_f32_e64 s[74:75], |v8|, s8
	s_nop 1
	v_cndmask_b32_e64 v8, v8, v15, s[74:75]
	v_cndmask_b32_e32 v15, 0, v47, vcc
	v_sub_f32_e32 v8, v8, v15
	v_min_f32_e32 v15, 0, v9
	v_mul_f32_e64 v9, |v9|, s96
	v_exp_f32_e32 v9, v9
	s_nop 0
	v_add_f32_e32 v9, 1.0, v9
	v_cmp_gt_f32_e32 vcc, s97, v9
	s_nop 1
	v_cndmask_b32_e64 v16, 0, 32, vcc
	v_ldexp_f32 v9, v9, v16
	v_log_f32_e32 v9, v9
	s_nop 0
	v_mul_f32_e32 v16, 0x3f317217, v9
	v_fma_f32 v16, v9, s92, -v16
	v_fmac_f32_e32 v16, 0x3377d1cf, v9
	v_fmac_f32_e32 v16, 0x3f317217, v9
	v_cmp_lt_f32_e64 s[74:75], |v9|, s8
	s_nop 1
	v_cndmask_b32_e64 v9, v9, v16, s[74:75]
	v_cndmask_b32_e32 v16, 0, v47, vcc
	v_sub_f32_e32 v9, v9, v16
	v_pk_add_f32 v[8:9], v[14:15], v[8:9] neg_lo:[0,1] neg_hi:[0,1]
	v_pk_mul_f32 v[8:9], v[8:9], s[6:7] op_sel_hi:[1,0]
	ds_write2_b32 v13, v8, v9 offset0:2 offset1:3
	v_min_f32_e32 v8, 0, v6
	v_mul_f32_e64 v6, |v6|, s96
	v_exp_f32_e32 v6, v6
	s_nop 0
	v_add_f32_e32 v6, 1.0, v6
	v_cmp_gt_f32_e32 vcc, s97, v6
	s_nop 1
	v_cndmask_b32_e64 v9, 0, 32, vcc
	v_ldexp_f32 v6, v6, v9
	v_log_f32_e32 v6, v6
	s_nop 0
	v_mul_f32_e32 v9, 0x3f317217, v6
	v_fma_f32 v9, v6, s92, -v9
	v_fmac_f32_e32 v9, 0x3377d1cf, v6
	v_fmac_f32_e32 v9, 0x3f317217, v6
	v_cmp_lt_f32_e64 s[74:75], |v6|, s8
	s_nop 1
	v_cndmask_b32_e64 v6, v6, v9, s[74:75]
	v_cndmask_b32_e32 v9, 0, v47, vcc
	v_sub_f32_e32 v6, v6, v9
	v_min_f32_e32 v9, 0, v7
	v_mul_f32_e64 v7, |v7|, s96
	v_exp_f32_e32 v7, v7
	s_nop 0
	v_add_f32_e32 v7, 1.0, v7
	v_cmp_gt_f32_e32 vcc, s97, v7
	s_nop 1
	v_cndmask_b32_e64 v14, 0, 32, vcc
	v_ldexp_f32 v7, v7, v14
	v_log_f32_e32 v7, v7
	s_nop 0
	v_mul_f32_e32 v14, 0x3f317217, v7
	v_fma_f32 v14, v7, s92, -v14
	v_fmac_f32_e32 v14, 0x3377d1cf, v7
	v_fmac_f32_e32 v14, 0x3f317217, v7
	v_cmp_lt_f32_e64 s[74:75], |v7|, s8
	s_nop 1
	v_cndmask_b32_e64 v7, v7, v14, s[74:75]
	v_cndmask_b32_e32 v14, 0, v47, vcc
	v_sub_f32_e32 v7, v7, v14
	v_pk_add_f32 v[6:7], v[8:9], v[6:7] neg_lo:[0,1] neg_hi:[0,1]
	v_pk_mul_f32 v[6:7], v[6:7], s[6:7] op_sel_hi:[1,0]
	ds_write2_b32 v13, v6, v7 offset0:4 offset1:5
	v_min_f32_e32 v6, 0, v4
	v_mul_f32_e64 v4, |v4|, s96
	v_exp_f32_e32 v4, v4
	s_nop 0
	v_add_f32_e32 v4, 1.0, v4
	v_cmp_gt_f32_e32 vcc, s97, v4
	s_nop 1
	v_cndmask_b32_e64 v7, 0, 32, vcc
	v_ldexp_f32 v4, v4, v7
	v_log_f32_e32 v4, v4
	s_nop 0
	v_mul_f32_e32 v7, 0x3f317217, v4
	v_fma_f32 v7, v4, s92, -v7
	v_fmac_f32_e32 v7, 0x3377d1cf, v4
	v_fmac_f32_e32 v7, 0x3f317217, v4
	v_cmp_lt_f32_e64 s[74:75], |v4|, s8
	s_nop 1
	v_cndmask_b32_e64 v4, v4, v7, s[74:75]
	v_cndmask_b32_e32 v7, 0, v47, vcc
	v_sub_f32_e32 v4, v4, v7
	v_min_f32_e32 v7, 0, v5
	v_mul_f32_e64 v5, |v5|, s96
	v_exp_f32_e32 v5, v5
	s_nop 0
	v_add_f32_e32 v5, 1.0, v5
	v_cmp_gt_f32_e32 vcc, s97, v5
	s_nop 1
	v_cndmask_b32_e64 v8, 0, 32, vcc
	v_ldexp_f32 v5, v5, v8
	v_log_f32_e32 v5, v5
	s_nop 0
	v_mul_f32_e32 v8, 0x3f317217, v5
	v_fma_f32 v8, v5, s92, -v8
	v_fmac_f32_e32 v8, 0x3377d1cf, v5
	v_fmac_f32_e32 v8, 0x3f317217, v5
	v_cmp_lt_f32_e64 s[74:75], |v5|, s8
	s_nop 1
	v_cndmask_b32_e64 v5, v5, v8, s[74:75]
	v_cndmask_b32_e32 v8, 0, v47, vcc
	v_sub_f32_e32 v5, v5, v8
	v_pk_add_f32 v[4:5], v[6:7], v[4:5] neg_lo:[0,1] neg_hi:[0,1]
	v_cmp_lt_i32_e32 vcc, 0, v17
	v_pk_mul_f32 v[4:5], v[4:5], s[6:7] op_sel_hi:[1,0]
	ds_write2_b32 v13, v4, v5 offset0:6 offset1:7
	v_and_b32_e32 v4, 63, v82
	v_lshl_add_u32 v14, v4, 2, 0
	v_mul_lo_u32 v4, v17, s0
	v_add_u32_e32 v4, v14, v4
	v_mov_b32_e32 v10, v82
	v_mov_b32_e32 v32, v102
	s_waitcnt vmcnt(0) lgkmcnt(0)
	s_branch .Lg1j_l1
